# plus rms_phase: gamma preloaded once, per-chunk vmcnt(0) store-ack waits removed
# speedup vs baseline: 1.0157x; 1.0157x over previous
; __device__ __forceinline__ unsigned cvt_pk_bf16(float lo, float hi) { f32x2_t f = {lo, hi}; bf16x2_t r = __builtin_convertvector(f, bf16x2_t); return __builtin_bit_cast(unsigned, r); }
; __device__ __forceinline__ void rms_phase(const float* X, const float* g, bf16_t* H, int gw, int NGW, int lane) {
;     for (int m = gw; m < M; m += 2 * NGW) {
;         const int m2 = m + NGW; const bool two = m2 < M;
;         const f32x4* xa = (const f32x4*)(X + (size_t)m * DM) + lane; const f32x4* xb = (const f32x4*)(X + (size_t)(two ? m2 : m) * DM) + lane; const f32x4* gr = (const f32x4*)g + lane;
;         f32x4 va[8], vb[8]; float sa = 0.f, sb = 0.f;
; #pragma unroll
;         for (int j = 0; j < 8; ++j) { va[j] = xa[64 * j]; vb[j] = xb[64 * j]; }
; #pragma unroll
;         for (int j = 0; j < 8; ++j) { sa += (va[j].x * va[j].x + va[j].y * va[j].y) + (va[j].z * va[j].z + va[j].w * va[j].w); sb += (vb[j].x * vb[j].x + vb[j].y * vb[j].y) + (vb[j].z * vb[j].z + vb[j].w * vb[j].w); }
;         const float ra = 1.0f / sqrtf(wave_sum(sa) * (1.0f / DM) + EPS), rb = 1.0f / sqrtf(wave_sum(sb) * (1.0f / DM) + EPS);
;         u32x2* oa = (u32x2*)(H + (size_t)m * DM) + lane; u32x2* ob = (u32x2*)(H + (size_t)m2 * DM) + lane;
; #pragma unroll
;         for (int j = 0; j < 8; ++j) { const f32x4 gg = gr[64 * j]; u32x2 w; w.x = cvt_pk_bf16(va[j].x * ra * gg.x, va[j].y * ra * gg.y); w.y = cvt_pk_bf16(va[j].z * ra * gg.z, va[j].w * ra * gg.w); oa[64 * j] = w;
.LBB0_61:
	s_cmpk_gt_i32 s6, 0x3fff
	v_mbcnt_lo_u32_b32 v186, -1, 0
	s_cbranch_scc1 .LBB0_80
	s_load_dwordx2 s[4:5], s[14:15], 0x0
	s_load_dwordx2 s[8:9], s[14:15], 0x18
	v_lshlrev_b32_e32 v0, 4, v92
	v_mov_b32_e32 v1, 0
	v_mov_b32_e32 v96, 0x260
	s_waitcnt lgkmcnt(0)
	v_lshl_add_u64 v[68:69], s[4:5], 0, v[0:1]
	v_lshl_add_u64 v[70:71], s[8:9], 0, v[0:1]
	v_mbcnt_hi_u32_b32 v0, -1, v186
	v_and_b32_e32 v2, 64, v0
	v_add_u32_e32 v2, 64, v2
	v_xor_b32_e32 v3, 1, v0
	v_cmp_lt_i32_e32 vcc, v3, v2
	s_mov_b64 s[4:5], 0x4300000
	s_nop 0
	v_cndmask_b32_e32 v3, v0, v3, vcc
	v_lshlrev_b32_e32 v85, 2, v3
	v_xor_b32_e32 v3, 2, v0
	v_cmp_lt_i32_e32 vcc, v3, v2
	s_nop 1
	v_cndmask_b32_e32 v3, v0, v3, vcc
	v_lshlrev_b32_e32 v90, 2, v3
	v_xor_b32_e32 v3, 4, v0
	v_cmp_lt_i32_e32 vcc, v3, v2
	s_nop 1
	v_cndmask_b32_e32 v3, v0, v3, vcc
	v_lshlrev_b32_e32 v91, 2, v3
	v_xor_b32_e32 v3, 8, v0
	v_cmp_lt_i32_e32 vcc, v3, v2
	s_nop 1
	v_cndmask_b32_e32 v3, v0, v3, vcc
	v_lshlrev_b32_e32 v93, 2, v3
	v_xor_b32_e32 v3, 16, v0
	v_cmp_lt_i32_e32 vcc, v3, v2
	s_nop 1
	v_cndmask_b32_e32 v3, v0, v3, vcc
	v_lshlrev_b32_e32 v94, 2, v3
	v_xor_b32_e32 v3, 32, v0
	v_cmp_lt_i32_e32 vcc, v3, v2
	s_nop 1
	v_cndmask_b32_e32 v0, v0, v3, vcc
	v_lshlrev_b32_e32 v95, 2, v0
	v_lshlrev_b32_e32 v0, 3, v92
	v_lshl_add_u64 v[0:1], s[12:13], 0, v[0:1]
	v_lshl_add_u64 v[72:73], v[0:1], 0, s[4:5]
	s_mov_b64 s[4:5], 0x1000
	v_lshl_add_u64 v[74:75], v[70:71], 0, s[4:5]
	s_mov_b64 s[4:5], 0x1400
	v_lshl_add_u64 v[76:77], v[70:71], 0, s[4:5]
	s_mov_b64 s[4:5], 0x1800
	v_lshl_add_u64 v[78:79], v[70:71], 0, s[4:5]
	s_mov_b64 s[4:5], 0x1c00
	v_lshl_add_u64 v[80:81], v[70:71], 0, s[4:5]
	s_movk_i32 s12, 0x1000
	v_mov_b32_e32 v92, 0x358637bd
	s_mov_b32 s13, 0xf800000
	global_load_dwordx4 v[140:143], v[70:71], off
	global_load_dwordx4 v[144:147], v[70:71], off offset:1024
	global_load_dwordx4 v[148:151], v[70:71], off offset:2048
	global_load_dwordx4 v[152:155], v[70:71], off offset:3072
	global_load_dwordx4 v[156:159], v[74:75], off
	global_load_dwordx4 v[160:163], v[76:77], off
	global_load_dwordx4 v[164:167], v[78:79], off
	global_load_dwordx4 v[168:171], v[80:81], off
	s_waitcnt vmcnt(0)
	s_branch .LBB0_64

; __device__ __forceinline__ void rms_phase(const float* X, const float* g, bf16_t* H, int gw, int NGW, int lane) {
;     for (int m = gw; m < M; m += 2 * NGW) {
;         const int m2 = m + NGW; const bool two = m2 < M;
;         const f32x4* xa = (const f32x4*)(X + (size_t)m * DM) + lane; const f32x4* xb = (const f32x4*)(X + (size_t)(two ? m2 : m) * DM) + lane; const f32x4* gr = (const f32x4*)g + lane;
;         f32x4 va[8], vb[8]; float sa = 0.f, sb = 0.f;
; #pragma unroll
;         for (int j = 0; j < 8; ++j) { va[j] = xa[64 * j]; vb[j] = xb[64 * j]; }
; #pragma unroll
;         for (int j = 0; j < 8; ++j) { sa += (va[j].x * va[j].x + va[j].y * va[j].y) + (va[j].z * va[j].z + va[j].w * va[j].w); sb += (vb[j].x * vb[j].x + vb[j].y * vb[j].y) + (vb[j].z * vb[j].z + vb[j].w * vb[j].w); }
;         const float ra = 1.0f / sqrtf(wave_sum(sa) * (1.0f / DM) + EPS), rb = 1.0f / sqrtf(wave_sum(sb) * (1.0f / DM) + EPS);
.LBB0_64:
	s_ashr_i32 s7, s6, 31
	s_lshl_b64 s[4:5], s[6:7], 13
	v_lshl_add_u64 v[0:1], v[68:69], 0, s[4:5]
	s_add_i32 s8, s6, s69
	global_load_dwordx4 v[56:59], v[0:1], off
	global_load_dwordx4 v[48:51], v[0:1], off offset:1024
	global_load_dwordx4 v[40:43], v[0:1], off offset:2048
	global_load_dwordx4 v[32:35], v[0:1], off offset:3072
	v_add_co_u32_e32 v0, vcc, s12, v0
	s_cmpk_lt_i32 s8, 0x4000
	s_nop 0
	v_addc_co_u32_e32 v1, vcc, 0, v1, vcc
	s_cselect_b64 s[10:11], -1, 0
	global_load_dwordx4 v[24:27], v[0:1], off
	global_load_dwordx4 v[20:23], v[0:1], off offset:1024
	s_and_b64 s[4:5], s[10:11], exec
	s_cselect_b32 s4, s8, s6
	s_ashr_i32 s5, s4, 31
	s_lshl_b64 s[4:5], s[4:5], 13
	v_lshl_add_u64 v[2:3], v[68:69], 0, s[4:5]
	global_load_dwordx4 v[60:63], v[2:3], off
	global_load_dwordx4 v[52:55], v[2:3], off offset:1024
	global_load_dwordx4 v[44:47], v[2:3], off offset:2048
	global_load_dwordx4 v[36:39], v[2:3], off offset:3072
	global_load_dwordx4 v[4:7], v[0:1], off offset:3072
	global_load_dwordx4 v[12:15], v[0:1], off offset:2048
	v_add_co_u32_e32 v64, vcc, s12, v2
	s_lshl_b64 s[14:15], s[6:7], 12
	s_nop 0
	v_addc_co_u32_e32 v65, vcc, 0, v3, vcc
	global_load_dwordx4 v[28:31], v[64:65], off
	global_load_dwordx4 v[16:19], v[64:65], off offset:1024
	global_load_dwordx4 v[8:11], v[64:65], off offset:2048
	global_load_dwordx4 v[0:3], v[64:65], off offset:3072
	s_ashr_i32 s9, s8, 31
	s_lshl_b64 s[18:19], s[8:9], 12
	s_cmpk_gt_i32 s8, 0x3fff
	s_waitcnt vmcnt(15)
	v_mov_b32_e32 v66, v57
	s_waitcnt vmcnt(14)
	v_mov_b32_e32 v67, v49
	v_mov_b32_e32 v86, v59
	v_mov_b32_e32 v87, v51
	v_mov_b32_e32 v64, v56
	v_mov_b32_e32 v65, v48
	v_mov_b32_e32 v82, v58
	v_mov_b32_e32 v83, v50
	s_waitcnt vmcnt(13)
	v_pk_mul_f32 v[88:89], v[42:43], v[42:43]
	v_pk_mul_f32 v[98:99], v[40:41], v[40:41]
	s_waitcnt vmcnt(12)
	v_mul_f32_e32 v84, v33, v33
	v_mul_f32_e32 v100, v35, v35
	v_pk_mul_f32 v[66:67], v[66:67], v[66:67]
	v_pk_mul_f32 v[86:87], v[86:87], v[86:87]
	v_pk_mov_b32 v[102:103], v[98:99], v[88:89] op_sel:[1,0]
	v_mov_b32_e32 v99, v89
	s_waitcnt vmcnt(11)
	v_mul_f32_e32 v109, v26, v26
	v_mul_f32_e32 v110, v27, v27
	v_pk_fma_f32 v[88:89], v[32:33], v[32:33], v[84:85] op_sel_hi:[1,1,0]
	v_pk_fma_f32 v[100:101], v[34:35], v[34:35], v[100:101] op_sel_hi:[1,1,0]
	v_pk_fma_f32 v[64:65], v[64:65], v[64:65], v[66:67]
	v_pk_fma_f32 v[66:67], v[82:83], v[82:83], v[86:87]
	v_pk_add_f32 v[82:83], v[102:103], v[98:99]
	v_mov_b32_e32 v89, v109
	v_mov_b32_e32 v101, v110
	v_pk_add_f32 v[64:65], v[64:65], v[66:67]
	v_mul_f32_e32 v97, v24, v24
	v_mul_f32_e32 v108, v25, v25
	v_pk_add_f32 v[66:67], v[82:83], v[82:83] op_sel:[0,1] op_sel_hi:[1,0]
	v_pk_add_f32 v[82:83], v[88:89], v[100:101]
	v_pk_add_f32 v[64:65], v[64:65], v[64:65] op_sel:[0,1] op_sel_hi:[1,0]
	s_waitcnt vmcnt(9)
	v_mul_f32_e32 v84, v61, v61
	v_mul_f32_e32 v86, v63, v63
	s_waitcnt vmcnt(8)
	v_mul_f32_e32 v87, v53, v53
	v_mul_f32_e32 v88, v55, v55
	v_mov_b32_e32 v67, v108
	v_mov_b32_e32 v65, v97
	s_waitcnt vmcnt(7)
	v_mul_f32_e32 v89, v45, v45
	v_mul_f32_e32 v97, v47, v47
	v_fmac_f32_e32 v84, v60, v60
	v_fmac_f32_e32 v86, v62, v62
	v_fmac_f32_e32 v87, v52, v52
	v_fmac_f32_e32 v88, v54, v54
	s_waitcnt vmcnt(6)
	v_mul_f32_e32 v98, v37, v37
	v_mul_f32_e32 v99, v39, v39
	v_pk_add_f32 v[64:65], v[64:65], v[66:67]
	v_fmac_f32_e32 v89, v44, v44
	v_fmac_f32_e32 v97, v46, v46
	v_add_f32_e32 v66, v84, v86
	v_add_f32_e32 v67, v87, v88
	v_fmac_f32_e32 v98, v36, v36
	v_fmac_f32_e32 v99, v38, v38
	v_pk_add_f32 v[64:65], v[64:65], v[82:83]
	v_add_f32_e32 v82, v89, v97
	v_add_f32_e32 v66, v66, v67
	v_pk_mul_f32 v[104:105], v[22:23], v[22:23]
	v_pk_mul_f32 v[106:107], v[20:21], v[20:21]
	v_add_f32_e32 v83, v98, v99
	v_add_f32_e32 v66, v66, v82
	v_add_f32_e32 v84, v66, v83
	v_pk_mov_b32 v[66:67], v[106:107], v[104:105] op_sel:[1,0]
	v_mov_b32_e32 v107, v105
	v_pk_add_f32 v[66:67], v[66:67], v[106:107]
	s_waitcnt vmcnt(5)
	v_mul_f32_e32 v82, v4, v4
	v_mul_f32_e32 v83, v5, v5
	v_pk_add_f32 v[64:65], v[64:65], v[64:65] op_sel:[0,1] op_sel_hi:[1,0]
	v_pk_add_f32 v[66:67], v[66:67], v[66:67] op_sel:[0,1] op_sel_hi:[1,0]
	v_mov_b32_e32 v65, v82
	v_mov_b32_e32 v67, v83
	v_pk_add_f32 v[64:65], v[64:65], v[66:67]
	s_waitcnt vmcnt(4)
	v_mul_f32_e32 v66, v13, v13
	v_mul_f32_e32 v82, v15, v15
	v_mul_f32_e32 v86, v6, v6
	v_mul_f32_e32 v87, v7, v7
	v_pk_fma_f32 v[66:67], v[12:13], v[12:13], v[66:67] op_sel_hi:[1,1,0]
	v_pk_fma_f32 v[82:83], v[14:15], v[14:15], v[82:83] op_sel_hi:[1,1,0]
	v_mov_b32_e32 v67, v86
	v_mov_b32_e32 v83, v87
	v_pk_add_f32 v[66:67], v[66:67], v[82:83]
	s_waitcnt vmcnt(2)
	v_mul_f32_e32 v82, v19, v19
	v_pk_add_f32 v[64:65], v[64:65], v[66:67]
	v_mul_f32_e32 v66, v29, v29
	v_add_f32_e32 v64, v64, v65
	ds_bpermute_b32 v65, v85, v64
	v_mul_f32_e32 v67, v31, v31
	v_fmac_f32_e32 v66, v28, v28
	v_fmac_f32_e32 v67, v30, v30
	v_add_f32_e32 v66, v66, v67
	s_waitcnt lgkmcnt(0)
	v_add_f32_e32 v64, v64, v65
	ds_bpermute_b32 v65, v90, v64
	v_mul_f32_e32 v67, v17, v17
	v_fmac_f32_e32 v67, v16, v16
	v_fmac_f32_e32 v82, v18, v18
	v_add_f32_e32 v66, v84, v66
	s_waitcnt lgkmcnt(0)
	v_add_f32_e32 v64, v64, v65
	ds_bpermute_b32 v65, v91, v64
	v_add_f32_e32 v67, v67, v82
	v_add_f32_e32 v66, v66, v67
	s_waitcnt vmcnt(1)
	v_mul_f32_e32 v67, v9, v9
	v_mul_f32_e32 v82, v11, v11
	s_waitcnt lgkmcnt(0)
	v_add_f32_e32 v64, v64, v65
	ds_bpermute_b32 v65, v93, v64
	v_fmac_f32_e32 v67, v8, v8
	v_fmac_f32_e32 v82, v10, v10
	v_add_f32_e32 v67, v67, v82
	v_add_f32_e32 v66, v66, v67
	s_waitcnt lgkmcnt(0)
	v_add_f32_e32 v64, v64, v65
	ds_bpermute_b32 v65, v94, v64
	s_waitcnt vmcnt(0)
	v_mul_f32_e32 v67, v1, v1
	v_mul_f32_e32 v82, v3, v3
	v_fmac_f32_e32 v67, v0, v0
	v_fmac_f32_e32 v82, v2, v2
	s_waitcnt lgkmcnt(0)
; __device__ __forceinline__ unsigned cvt_pk_bf16(float lo, float hi) { f32x2_t f = {lo, hi}; bf16x2_t r = __builtin_convertvector(f, bf16x2_t); return __builtin_bit_cast(unsigned, r); }
; __device__ __forceinline__ void rms_phase(const float* X, const float* g, bf16_t* H, int gw, int NGW, int lane) {
;     ...
;         const float ra = 1.0f / sqrtf(wave_sum(sa) * (1.0f / DM) + EPS), rb = 1.0f / sqrtf(wave_sum(sb) * (1.0f / DM) + EPS);
;         u32x2* oa = (u32x2*)(H + (size_t)m * DM) + lane; u32x2* ob = (u32x2*)(H + (size_t)m2 * DM) + lane;
; #pragma unroll
;         for (int j = 0; j < 8; ++j) { const f32x4 gg = gr[64 * j]; u32x2 w; w.x = cvt_pk_bf16(va[j].x * ra * gg.x, va[j].y * ra * gg.y); w.y = cvt_pk_bf16(va[j].z * ra * gg.z, va[j].w * ra * gg.w); oa[64 * j] = w;
;             if (two) { u32x2 w2; w2.x = cvt_pk_bf16(vb[j].x * rb * gg.x, vb[j].y * rb * gg.y); w2.y = cvt_pk_bf16(vb[j].z * rb * gg.z, vb[j].w * rb * gg.w); ob[64 * j] = w2; } }
	v_add_f32_e32 v64, v64, v65
	ds_bpermute_b32 v65, v95, v64
	v_add_f32_e32 v67, v67, v82
	v_add_f32_e32 v82, v66, v67
	ds_bpermute_b32 v86, v85, v82
	s_waitcnt lgkmcnt(1)
	v_add_f32_e32 v64, v64, v65
	v_fmamk_f32 v83, v64, 0x3a000000, v92
	s_nop 1
	v_mov_b64_e32 v[64:65], v[140:141]
	v_mov_b64_e32 v[66:67], v[142:143]
	s_waitcnt lgkmcnt(0)
	v_add_f32_e32 v82, v82, v86
	ds_bpermute_b32 v86, v90, v82
	v_mul_f32_e32 v84, 0x4f800000, v83
	v_cmp_gt_f32_e32 vcc, s13, v83
	s_waitcnt lgkmcnt(0)
	v_add_f32_e32 v82, v82, v86
	ds_bpermute_b32 v86, v91, v82
	v_cndmask_b32_e32 v83, v83, v84, vcc
	v_sqrt_f32_e32 v84, v83
	s_waitcnt lgkmcnt(0)
	v_add_f32_e32 v82, v82, v86
	ds_bpermute_b32 v86, v93, v82
	v_add_u32_e32 v87, -1, v84
	v_fma_f32 v88, -v87, v84, v83
	v_cmp_ge_f32_e64 s[4:5], 0, v88
	v_add_u32_e32 v88, 1, v84
	s_waitcnt lgkmcnt(0)
	v_add_f32_e32 v82, v82, v86
	ds_bpermute_b32 v86, v94, v82
	v_cndmask_b32_e64 v87, v84, v87, s[4:5]
	v_fma_f32 v84, -v88, v84, v83
	v_cmp_lt_f32_e64 s[4:5], 0, v84
	s_waitcnt lgkmcnt(0)
	v_add_f32_e32 v82, v82, v86
	v_cndmask_b32_e64 v84, v87, v88, s[4:5]
	v_mul_f32_e32 v87, 0x37800000, v84
	ds_bpermute_b32 v86, v95, v82
	v_cndmask_b32_e32 v84, v84, v87, vcc
	v_cmp_class_f32_e32 vcc, v83, v96
	s_waitcnt lgkmcnt(0)
	v_add_f32_e32 v82, v82, v86
	v_cndmask_b32_e32 v83, v84, v83, vcc
	v_div_scale_f32 v84, s[4:5], v83, v83, 1.0
	v_rcp_f32_e32 v87, v84
	v_fmamk_f32 v82, v82, 0x3a000000, v92
	v_mul_f32_e32 v86, 0x4f800000, v82
	v_cmp_gt_f32_e64 s[4:5], s13, v82
	v_fma_f32 v88, -v84, v87, 1.0
	v_fmac_f32_e32 v87, v88, v87
	v_cndmask_b32_e64 v82, v82, v86, s[4:5]
	v_div_scale_f32 v88, vcc, 1.0, v83, 1.0
	v_sqrt_f32_e32 v86, v82
	v_mul_f32_e32 v89, v88, v87
	v_fma_f32 v97, -v84, v89, v88
	v_fmac_f32_e32 v89, v97, v87
	v_fma_f32 v84, -v84, v89, v88
	v_add_u32_e32 v88, -1, v86
	v_fma_f32 v97, -v88, v86, v82
	v_cmp_ge_f32_e64 s[6:7], 0, v97
	v_add_u32_e32 v97, 1, v86
	v_div_fmas_f32 v84, v84, v87, v89
	v_cndmask_b32_e64 v88, v86, v88, s[6:7]
	v_fma_f32 v86, -v97, v86, v82
	v_cmp_lt_f32_e64 s[6:7], 0, v86
	s_nop 1
	v_cndmask_b32_e64 v86, v88, v97, s[6:7]
	v_mul_f32_e32 v88, 0x37800000, v86
	v_cndmask_b32_e64 v86, v86, v88, s[4:5]
	v_cmp_class_f32_e64 s[4:5], v82, v96
	v_div_fixup_f32 v88, v84, v83, 1.0
	v_pk_mul_f32 v[56:57], v[56:57], v[88:89] op_sel_hi:[1,0]
	v_cndmask_b32_e64 v82, v86, v82, s[4:5]
	v_div_scale_f32 v86, s[4:5], v82, v82, 1.0
	v_rcp_f32_e32 v97, v86
	v_pk_mul_f32 v[58:59], v[58:59], v[88:89] op_sel_hi:[1,0]
	v_fma_f32 v83, -v86, v97, 1.0
	v_fmac_f32_e32 v97, v83, v97
	v_div_scale_f32 v83, vcc, 1.0, v82, 1.0
	v_mul_f32_e32 v84, v83, v97
	v_fma_f32 v87, -v86, v84, v83
	v_fmac_f32_e32 v84, v87, v97
	v_fma_f32 v83, -v86, v84, v83
	v_div_fmas_f32 v83, v83, v97, v84
	v_pk_mul_f32 v[56:57], v[64:65], v[56:57]
	v_pk_mul_f32 v[58:59], v[66:67], v[58:59]
	v_div_fixup_f32 v84, v83, v82, 1.0
	v_lshl_add_u64 v[86:87], v[72:73], 0, s[14:15]
	v_lshl_add_u64 v[82:83], v[72:73], 0, s[18:19]
	v_cvt_pk_bf16_f32 v56, v56, v57
	v_cvt_pk_bf16_f32 v57, v58, v59
	global_store_dwordx2 v[86:87], v[56:57], off
	s_cbranch_scc1 .LBB0_66
	v_pk_mul_f32 v[56:57], v[60:61], v[84:85] op_sel_hi:[1,0]
	v_pk_mul_f32 v[58:59], v[62:63], v[84:85] op_sel_hi:[1,0]
	v_pk_mul_f32 v[56:57], v[64:65], v[56:57]
	v_pk_mul_f32 v[58:59], v[66:67], v[58:59]
	v_cvt_pk_bf16_f32 v56, v56, v57
	v_cvt_pk_bf16_f32 v57, v58, v59
	global_store_dwordx2 v[82:83], v[56:57], off
.LBB0_66:
	s_nop 1
	v_mov_b64_e32 v[56:57], v[144:145]
	v_mov_b64_e32 v[58:59], v[146:147]
	v_mov_b32_e32 v89, v88
	v_pk_mul_f32 v[48:49], v[48:49], v[88:89]
	v_pk_mul_f32 v[50:51], v[50:51], v[88:89]
	v_cndmask_b32_e64 v60, 0, 1, s[10:11]
	v_cmp_ne_u32_e64 s[4:5], 1, v60
	s_andn2_b64 vcc, exec, s[10:11]
	v_pk_mul_f32 v[48:49], v[48:49], v[56:57]
	v_pk_mul_f32 v[50:51], v[50:51], v[58:59]
	v_cvt_pk_bf16_f32 v48, v48, v49
	v_cvt_pk_bf16_f32 v49, v50, v51
	global_store_dwordx2 v[86:87], v[48:49], off offset:512
	s_cbranch_vccnz .LBB0_68
	v_pk_mul_f32 v[48:49], v[52:53], v[84:85] op_sel_hi:[1,0]
	v_pk_mul_f32 v[50:51], v[54:55], v[84:85] op_sel_hi:[1,0]
	v_pk_mul_f32 v[48:49], v[48:49], v[56:57]
	v_pk_mul_f32 v[50:51], v[50:51], v[58:59]
	v_cvt_pk_bf16_f32 v48, v48, v49
	v_cvt_pk_bf16_f32 v49, v50, v51
	global_store_dwordx2 v[82:83], v[48:49], off offset:512
; __device__ __forceinline__ unsigned cvt_pk_bf16(float lo, float hi) { f32x2_t f = {lo, hi}; bf16x2_t r = __builtin_convertvector(f, bf16x2_t); return __builtin_bit_cast(unsigned, r); }
; __device__ __forceinline__ void rms_phase(const float* X, const float* g, bf16_t* H, int gw, int NGW, int lane) {
;     ...
; #pragma unroll
;         for (int j = 0; j < 8; ++j) { const f32x4 gg = gr[64 * j]; u32x2 w; w.x = cvt_pk_bf16(va[j].x * ra * gg.x, va[j].y * ra * gg.y); w.y = cvt_pk_bf16(va[j].z * ra * gg.z, va[j].w * ra * gg.w); oa[64 * j] = w;
;             if (two) { u32x2 w2; w2.x = cvt_pk_bf16(vb[j].x * rb * gg.x, vb[j].y * rb * gg.y); w2.y = cvt_pk_bf16(vb[j].z * rb * gg.z, vb[j].w * rb * gg.w); ob[64 * j] = w2; } }
.LBB0_68:
	s_nop 1
	v_mov_b64_e32 v[48:49], v[148:149]
	v_mov_b64_e32 v[50:51], v[150:151]
	v_pk_mul_f32 v[40:41], v[40:41], v[88:89]
	v_pk_mul_f32 v[42:43], v[42:43], v[88:89]
	s_and_b64 vcc, exec, s[4:5]
	v_pk_mul_f32 v[40:41], v[40:41], v[48:49]
	v_pk_mul_f32 v[42:43], v[42:43], v[50:51]
	v_cvt_pk_bf16_f32 v40, v40, v41
	v_cvt_pk_bf16_f32 v41, v42, v43
	global_store_dwordx2 v[86:87], v[40:41], off offset:1024
	s_cbranch_vccnz .LBB0_70
	v_pk_mul_f32 v[40:41], v[44:45], v[84:85] op_sel_hi:[1,0]
	v_pk_mul_f32 v[42:43], v[46:47], v[84:85] op_sel_hi:[1,0]
	v_pk_mul_f32 v[40:41], v[40:41], v[48:49]
	v_pk_mul_f32 v[42:43], v[42:43], v[50:51]
	v_cvt_pk_bf16_f32 v40, v40, v41
	v_cvt_pk_bf16_f32 v41, v42, v43
	global_store_dwordx2 v[82:83], v[40:41], off offset:1024
.LBB0_70:
	s_nop 1
	v_mov_b64_e32 v[40:41], v[152:153]
	v_mov_b64_e32 v[42:43], v[154:155]
	v_pk_mul_f32 v[32:33], v[32:33], v[88:89]
	v_pk_mul_f32 v[34:35], v[34:35], v[88:89]
	s_and_b64 vcc, exec, s[4:5]
	v_pk_mul_f32 v[32:33], v[32:33], v[40:41]
	v_pk_mul_f32 v[34:35], v[34:35], v[42:43]
	v_cvt_pk_bf16_f32 v32, v32, v33
	v_cvt_pk_bf16_f32 v33, v34, v35
	global_store_dwordx2 v[86:87], v[32:33], off offset:1536
	s_cbranch_vccnz .LBB0_72
	v_pk_mul_f32 v[32:33], v[36:37], v[84:85] op_sel_hi:[1,0]
	v_pk_mul_f32 v[34:35], v[38:39], v[84:85] op_sel_hi:[1,0]
	v_pk_mul_f32 v[32:33], v[32:33], v[40:41]
	v_pk_mul_f32 v[34:35], v[34:35], v[42:43]
	v_cvt_pk_bf16_f32 v32, v32, v33
	v_cvt_pk_bf16_f32 v33, v34, v35
	global_store_dwordx2 v[82:83], v[32:33], off offset:1536
.LBB0_72:
	s_nop 1
	v_mov_b64_e32 v[32:33], v[156:157]
	v_mov_b64_e32 v[34:35], v[158:159]
	v_pk_mul_f32 v[24:25], v[24:25], v[88:89]
	v_pk_mul_f32 v[26:27], v[26:27], v[88:89]
	s_and_b64 vcc, exec, s[4:5]
	v_pk_mul_f32 v[24:25], v[24:25], v[32:33]
	v_pk_mul_f32 v[26:27], v[26:27], v[34:35]
	v_cvt_pk_bf16_f32 v24, v24, v25
	v_cvt_pk_bf16_f32 v25, v26, v27
	global_store_dwordx2 v[86:87], v[24:25], off offset:2048
	s_cbranch_vccnz .LBB0_74
	v_pk_mul_f32 v[24:25], v[28:29], v[84:85] op_sel_hi:[1,0]
	v_pk_mul_f32 v[26:27], v[30:31], v[84:85] op_sel_hi:[1,0]
	v_pk_mul_f32 v[24:25], v[24:25], v[32:33]
	v_pk_mul_f32 v[26:27], v[26:27], v[34:35]
	v_cvt_pk_bf16_f32 v24, v24, v25
	v_cvt_pk_bf16_f32 v25, v26, v27
	global_store_dwordx2 v[82:83], v[24:25], off offset:2048
.LBB0_74:
	s_nop 1
	v_mov_b64_e32 v[24:25], v[160:161]
	v_mov_b64_e32 v[26:27], v[162:163]
	v_pk_mul_f32 v[20:21], v[20:21], v[88:89]
	v_pk_mul_f32 v[22:23], v[22:23], v[88:89]
	s_and_b64 vcc, exec, s[4:5]
	v_pk_mul_f32 v[20:21], v[20:21], v[24:25]
	v_pk_mul_f32 v[22:23], v[22:23], v[26:27]
	v_cvt_pk_bf16_f32 v20, v20, v21
	v_cvt_pk_bf16_f32 v21, v22, v23
	global_store_dwordx2 v[86:87], v[20:21], off offset:2560
	s_cbranch_vccnz .LBB0_76
	v_pk_mul_f32 v[16:17], v[16:17], v[84:85] op_sel_hi:[1,0]
	v_pk_mul_f32 v[18:19], v[18:19], v[84:85] op_sel_hi:[1,0]
	v_pk_mul_f32 v[16:17], v[16:17], v[24:25]
	v_pk_mul_f32 v[18:19], v[18:19], v[26:27]
	v_cvt_pk_bf16_f32 v16, v16, v17
	v_cvt_pk_bf16_f32 v17, v18, v19
	global_store_dwordx2 v[82:83], v[16:17], off offset:2560
.LBB0_76:
	s_nop 1
	v_mov_b64_e32 v[16:17], v[164:165]
	v_mov_b64_e32 v[18:19], v[166:167]
	v_pk_mul_f32 v[12:13], v[12:13], v[88:89]
	v_pk_mul_f32 v[14:15], v[14:15], v[88:89]
	s_and_b64 vcc, exec, s[4:5]
	v_pk_mul_f32 v[12:13], v[12:13], v[16:17]
	v_pk_mul_f32 v[14:15], v[14:15], v[18:19]
	v_cvt_pk_bf16_f32 v12, v12, v13
	v_cvt_pk_bf16_f32 v13, v14, v15
	global_store_dwordx2 v[86:87], v[12:13], off offset:3072
	s_cbranch_vccnz .LBB0_78
	v_pk_mul_f32 v[8:9], v[8:9], v[84:85] op_sel_hi:[1,0]
	v_pk_mul_f32 v[10:11], v[10:11], v[84:85] op_sel_hi:[1,0]
	v_pk_mul_f32 v[8:9], v[8:9], v[16:17]
	v_pk_mul_f32 v[10:11], v[10:11], v[18:19]
	v_cvt_pk_bf16_f32 v8, v8, v9
	v_cvt_pk_bf16_f32 v9, v10, v11
	global_store_dwordx2 v[82:83], v[8:9], off offset:3072
.LBB0_78:
	s_nop 1
	v_mov_b64_e32 v[8:9], v[168:169]
	v_mov_b64_e32 v[10:11], v[170:171]
	v_pk_mul_f32 v[4:5], v[4:5], v[88:89]
	v_pk_mul_f32 v[6:7], v[6:7], v[88:89]
	s_and_b64 vcc, exec, s[4:5]
	v_pk_mul_f32 v[4:5], v[4:5], v[8:9]
	v_pk_mul_f32 v[6:7], v[6:7], v[10:11]
	v_cvt_pk_bf16_f32 v4, v4, v5
	v_cvt_pk_bf16_f32 v5, v6, v7
	global_store_dwordx2 v[86:87], v[4:5], off offset:3584
	s_cbranch_vccnz .LBB0_63
	v_pk_mul_f32 v[0:1], v[0:1], v[84:85] op_sel_hi:[1,0]
	v_pk_mul_f32 v[2:3], v[2:3], v[84:85] op_sel_hi:[1,0]
	v_pk_mul_f32 v[0:1], v[0:1], v[8:9]
	v_pk_mul_f32 v[2:3], v[2:3], v[10:11]
	v_cvt_pk_bf16_f32 v0, v0, v1
	v_cvt_pk_bf16_f32 v1, v2, v3
	global_store_dwordx2 v[82:83], v[0:1], off offset:3584
	s_branch .LBB0_63
